# global seams: early un-waited write-back by local arrivers 16 and 28
# speedup vs baseline: 1.0045x; 1.0045x over previous
.Lxb0_194:
	s_or_b64 exec, exec, s[12:13]
	v_cvt_f32_u32_e32 v4, v2
	s_waitcnt vmcnt(0)
	v_readfirstlane_b32 s0, v3
	v_sub_u32_e32 v3, 0, v2
	v_rcp_iflag_f32_e32 v4, v4
	v_add_u32_e32 v5, s0, v1
	v_mul_f32_e32 v4, 0x4f7ffffe, v4
	v_cvt_u32_f32_e32 v4, v4
	v_mul_lo_u32 v1, v3, v4
	v_mul_hi_u32 v1, v4, v1
	v_add_u32_e32 v1, v4, v1
	v_mul_hi_u32 v1, v5, v1
	v_mul_lo_u32 v3, v1, v2
	v_sub_u32_e32 v3, v5, v3
	v_add_u32_e32 v4, 1, v1
	v_cmp_ge_u32_e32 vcc, v3, v2
	s_nop 1
	v_cndmask_b32_e32 v1, v1, v4, vcc
	v_sub_u32_e32 v4, v3, v2
	v_cndmask_b32_e32 v3, v3, v4, vcc
	v_add_u32_e32 v4, 1, v1
	v_cmp_ge_u32_e32 vcc, v3, v2
	v_add_u32_e32 v3, 1, v5
	s_nop 0
	v_cndmask_b32_e32 v1, v1, v4, vcc
	v_mul_lo_u32 v4, v2, v1
	v_add_u32_e32 v2, v4, v2
	v_sub_u32_e32 v4, v5, v4
	v_add_u32_e32 v5, -16, v4
	v_add_u32_e32 v4, -28, v4
	v_mul_lo_u32 v4, v4, v5
	v_cmp_eq_u32_e32 vcc, 0, v4
	s_cbranch_vccz .Lefl_0
	buffer_wbl2 sc1

.LBB0_735:
	s_or_b64 exec, exec, s[14:15]
	v_cvt_f32_u32_e32 v4, v2
	s_waitcnt vmcnt(0)
	v_readfirstlane_b32 s0, v3
	v_sub_u32_e32 v3, 0, v2
	v_rcp_iflag_f32_e32 v4, v4
	v_add_u32_e32 v5, s0, v1
	v_mul_f32_e32 v4, 0x4f7ffffe, v4
	v_cvt_u32_f32_e32 v4, v4
	v_mul_lo_u32 v1, v3, v4
	v_mul_hi_u32 v1, v4, v1
	v_add_u32_e32 v1, v4, v1
	v_mul_hi_u32 v1, v5, v1
	v_mul_lo_u32 v3, v1, v2
	v_sub_u32_e32 v3, v5, v3
	v_add_u32_e32 v4, 1, v1
	v_cmp_ge_u32_e32 vcc, v3, v2
	s_nop 1
	v_cndmask_b32_e32 v1, v1, v4, vcc
	v_sub_u32_e32 v4, v3, v2
	v_cndmask_b32_e32 v3, v3, v4, vcc
	v_add_u32_e32 v4, 1, v1
	v_cmp_ge_u32_e32 vcc, v3, v2
	v_add_u32_e32 v3, 1, v5
	s_nop 0
	v_cndmask_b32_e32 v1, v1, v4, vcc
	v_mul_lo_u32 v4, v2, v1
	v_add_u32_e32 v2, v4, v2
	v_sub_u32_e32 v4, v5, v4
	v_add_u32_e32 v5, -16, v4
	v_add_u32_e32 v4, -28, v4
	v_mul_lo_u32 v4, v4, v5
	v_cmp_eq_u32_e32 vcc, 0, v4
	s_cbranch_vccz .Lefl_7
	buffer_wbl2 sc1

.LBB0_1040:
	s_or_b64 exec, exec, s[10:11]
	v_cvt_f32_u32_e32 v4, v2
	s_waitcnt vmcnt(0)
	v_readfirstlane_b32 s3, v3
	v_sub_u32_e32 v3, 0, v2
	v_rcp_iflag_f32_e32 v4, v4
	v_add_u32_e32 v5, s3, v1
	v_mul_f32_e32 v4, 0x4f7ffffe, v4
	v_cvt_u32_f32_e32 v4, v4
	v_mul_lo_u32 v1, v3, v4
	v_mul_hi_u32 v1, v4, v1
	v_add_u32_e32 v1, v4, v1
	v_mul_hi_u32 v1, v5, v1
	v_mul_lo_u32 v3, v1, v2
	v_sub_u32_e32 v3, v5, v3
	v_add_u32_e32 v4, 1, v1
	v_cmp_ge_u32_e32 vcc, v3, v2
	s_nop 1
	v_cndmask_b32_e32 v1, v1, v4, vcc
	v_sub_u32_e32 v4, v3, v2
	v_cndmask_b32_e32 v3, v3, v4, vcc
	v_add_u32_e32 v4, 1, v1
	v_cmp_ge_u32_e32 vcc, v3, v2
	v_add_u32_e32 v3, 1, v5
	s_nop 0
	v_cndmask_b32_e32 v1, v1, v4, vcc
	v_mul_lo_u32 v4, v2, v1
	v_add_u32_e32 v2, v4, v2
	v_sub_u32_e32 v4, v5, v4
	v_add_u32_e32 v5, -16, v4
	v_add_u32_e32 v4, -28, v4
	v_mul_lo_u32 v4, v4, v5
	v_cmp_eq_u32_e32 vcc, 0, v4
	s_cbranch_vccz .Lefl_10
	buffer_wbl2 sc1
